# lever 2 on the S5 Toeplitz set-up loop: four p-iterations per trip with their 16 scalar loads issued together (one latency window per 4 iterations instead of one per iteration)
# baseline (speedup 1.0000x reference)
.LBB0_419:
	global_load_dword v68, v[36:37], off
	global_load_dword v69, v[36:37], off offset:64
	global_load_dword v70, v[36:37], off offset:128
	global_load_dword v71, v[36:37], off offset:192
	global_load_dword v72, v[42:43], off
	global_load_dword v73, v[42:43], off offset:64
	global_load_dword v74, v[42:43], off offset:128
	global_load_dword v75, v[42:43], off offset:192
	v_lshl_add_u64 v[4:5], v[28:29], 0, s[6:7]
	v_lshl_add_u64 v[2:3], v[30:31], 0, s[6:7]
	global_load_dwordx4 v[76:79], v[4:5], off
	global_load_dwordx4 v[80:83], v[2:3], off
	s_add_u32 s6, s6, 16
	s_addc_u32 s7, s7, 0
	v_lshl_add_u64 v[36:37], v[36:37], 0, 64
	v_lshl_add_u64 v[42:43], v[42:43], 0, 64
	v_lshl_add_u64 v[36:37], v[36:37], 0, 64
	v_lshl_add_u64 v[42:43], v[42:43], 0, 64
	v_lshl_add_u64 v[36:37], v[36:37], 0, 64
	v_lshl_add_u64 v[42:43], v[42:43], 0, 64
	v_lshl_add_u64 v[36:37], v[36:37], 0, 64
	v_lshl_add_u64 v[42:43], v[42:43], 0, 64
	s_cmpk_eq_i32 s6, 0x100
	ds_read_b128 v[2:5], v56
	v_add_u32_e32 v56, 16, v56
	s_waitcnt vmcnt(0)
	v_mov_b32_e32 v58, v68
	v_mov_b32_e32 v60, v72
	v_mov_b32_e32 v62, v76
	v_mov_b32_e32 v64, v80
	s_waitcnt lgkmcnt(0)
	v_pk_mul_f32 v[58:59], v[4:5], v[58:59] op_sel_hi:[1,0]
	v_pk_fma_f32 v[66:67], v[4:5], v[60:61], v[58:59] op_sel:[1,0,0] op_sel_hi:[0,0,1]
	v_pk_fma_f32 v[4:5], v[4:5], v[60:61], v[58:59] op_sel:[1,0,0] op_sel_hi:[0,0,1] neg_lo:[0,0,1] neg_hi:[0,0,1]
	v_mov_b32_e32 v59, v5
	v_pk_mov_b32 v[4:5], v[4:5], v[66:67] op_sel:[1,0]
	v_mov_b32_e32 v58, v66
	v_pk_mul_f32 v[4:5], v[4:5], v[62:63] op_sel_hi:[1,0]
	v_pk_fma_f32 v[60:61], v[64:65], v[58:59], v[4:5] op_sel_hi:[0,1,1]
	v_pk_fma_f32 v[4:5], v[64:65], v[58:59], v[4:5] op_sel_hi:[0,1,1] neg_lo:[0,0,1] neg_hi:[0,0,1]
	v_mov_b32_e32 v58, v60
	v_mov_b32_e32 v59, v5
	v_pk_mov_b32 v[62:63], v[4:5], v[60:61] op_sel:[1,0]
	v_mul_f32_e32 v60, v3, v60
	v_pk_fma_f32 v[60:61], v[2:3], v[62:63], v[60:61] op_sel_hi:[1,1,0] neg_lo:[0,0,1] neg_hi:[0,0,1]
	v_pk_mul_f32 v[58:59], v[2:3], v[58:59]
	v_pk_mov_b32 v[4:5], v[4:5], v[60:61] op_sel:[1,0]
	v_pk_add_f32 v[58:59], v[58:59], v[58:59] op_sel:[0,1] op_sel_hi:[0,1]
	v_pk_add_f32 v[40:41], v[40:41], v[4:5]
	v_pk_mul_f32 v[4:5], v[2:3], v[58:59]
	s_nop 0
	v_pk_fma_f32 v[58:59], v[2:3], v[60:61], v[4:5] op_sel:[1,0,0] op_sel_hi:[0,0,1]
	v_pk_fma_f32 v[4:5], v[2:3], v[60:61], v[4:5] op_sel:[1,0,0] op_sel_hi:[0,0,1] neg_lo:[0,0,1] neg_hi:[0,0,1]
	v_mov_b32_e32 v60, v58
	v_mov_b32_e32 v61, v5
	v_pk_mov_b32 v[62:63], v[4:5], v[58:59] op_sel:[1,0]
	v_mul_f32_e32 v58, v3, v58
	v_pk_fma_f32 v[58:59], v[2:3], v[62:63], v[58:59] op_sel_hi:[1,1,0] neg_lo:[0,0,1] neg_hi:[0,0,1]
	v_pk_mul_f32 v[60:61], v[2:3], v[60:61]
	v_pk_mov_b32 v[4:5], v[4:5], v[58:59] op_sel:[1,0]
	v_pk_add_f32 v[60:61], v[60:61], v[60:61] op_sel:[0,1] op_sel_hi:[0,1]
	v_pk_add_f32 v[38:39], v[38:39], v[4:5]
	v_pk_mul_f32 v[4:5], v[2:3], v[60:61]
	s_nop 0
	v_pk_fma_f32 v[60:61], v[2:3], v[58:59], v[4:5] op_sel:[1,0,0] op_sel_hi:[0,0,1]
	v_pk_fma_f32 v[4:5], v[2:3], v[58:59], v[4:5] op_sel:[1,0,0] op_sel_hi:[0,0,1] neg_lo:[0,0,1] neg_hi:[0,0,1]
	v_mov_b32_e32 v58, v60
	v_mov_b32_e32 v59, v5
	v_pk_mov_b32 v[62:63], v[4:5], v[60:61] op_sel:[1,0]
	v_mul_f32_e32 v60, v3, v60
	v_pk_fma_f32 v[60:61], v[2:3], v[62:63], v[60:61] op_sel_hi:[1,1,0] neg_lo:[0,0,1] neg_hi:[0,0,1]
	v_pk_mul_f32 v[58:59], v[2:3], v[58:59]
	v_pk_mov_b32 v[4:5], v[4:5], v[60:61] op_sel:[1,0]
	v_pk_add_f32 v[58:59], v[58:59], v[58:59] op_sel:[0,1] op_sel_hi:[0,1]
	v_pk_add_f32 v[34:35], v[34:35], v[4:5]
	v_pk_mul_f32 v[4:5], v[2:3], v[58:59]
	s_nop 0
	v_pk_fma_f32 v[58:59], v[2:3], v[60:61], v[4:5] op_sel:[1,0,0] op_sel_hi:[0,0,1]
	v_pk_fma_f32 v[4:5], v[2:3], v[60:61], v[4:5] op_sel:[1,0,0] op_sel_hi:[0,0,1] neg_lo:[0,0,1] neg_hi:[0,0,1]
	v_mov_b32_e32 v60, v58
	v_mov_b32_e32 v61, v5
	v_pk_mov_b32 v[62:63], v[4:5], v[58:59] op_sel:[1,0]
	v_mul_f32_e32 v58, v3, v58
	v_pk_fma_f32 v[58:59], v[2:3], v[62:63], v[58:59] op_sel_hi:[1,1,0] neg_lo:[0,0,1] neg_hi:[0,0,1]
	v_pk_mul_f32 v[60:61], v[2:3], v[60:61]
	v_pk_mov_b32 v[4:5], v[4:5], v[58:59] op_sel:[1,0]
	v_pk_add_f32 v[60:61], v[60:61], v[60:61] op_sel:[0,1] op_sel_hi:[0,1]
	v_pk_add_f32 v[32:33], v[32:33], v[4:5]
	v_pk_mul_f32 v[4:5], v[2:3], v[60:61]
	s_nop 0
	v_pk_fma_f32 v[60:61], v[2:3], v[58:59], v[4:5] op_sel:[1,0,0] op_sel_hi:[0,0,1]
	v_pk_fma_f32 v[4:5], v[2:3], v[58:59], v[4:5] op_sel:[1,0,0] op_sel_hi:[0,0,1] neg_lo:[0,0,1] neg_hi:[0,0,1]
	v_mov_b32_e32 v58, v60
	v_mov_b32_e32 v59, v5
	v_pk_mov_b32 v[62:63], v[4:5], v[60:61] op_sel:[1,0]
	v_mul_f32_e32 v60, v3, v60
	v_pk_fma_f32 v[60:61], v[2:3], v[62:63], v[60:61] op_sel_hi:[1,1,0] neg_lo:[0,0,1] neg_hi:[0,0,1]
	v_pk_mul_f32 v[58:59], v[2:3], v[58:59]
	v_pk_mov_b32 v[4:5], v[4:5], v[60:61] op_sel:[1,0]
	v_pk_add_f32 v[58:59], v[58:59], v[58:59] op_sel:[0,1] op_sel_hi:[0,1]
	v_pk_add_f32 v[26:27], v[26:27], v[4:5]
	v_pk_mul_f32 v[4:5], v[2:3], v[58:59] op_sel:[1,0] op_sel_hi:[0,1]
	v_pk_fma_f32 v[58:59], v[2:3], v[60:61], v[4:5] op_sel_hi:[1,0,1] neg_lo:[0,0,1] neg_hi:[0,0,1]
	v_pk_fma_f32 v[4:5], v[2:3], v[60:61], v[4:5] op_sel_hi:[1,0,1]
	v_mov_b32_e32 v60, v58
	v_mov_b32_e32 v61, v5
	v_pk_mov_b32 v[62:63], v[4:5], v[58:59] op_sel:[1,0]
	v_mul_f32_e32 v4, v3, v5
	v_pk_fma_f32 v[4:5], v[2:3], v[60:61], v[4:5] op_sel_hi:[1,1,0] neg_lo:[0,0,1] neg_hi:[0,0,1]
	v_pk_mul_f32 v[60:61], v[2:3], v[62:63]
	v_mov_b32_e32 v59, v4
	v_pk_add_f32 v[60:61], v[60:61], v[60:61] op_sel:[0,1] op_sel_hi:[0,1]
	v_pk_add_f32 v[24:25], v[24:25], v[58:59]
	v_pk_mul_f32 v[58:59], v[2:3], v[60:61] op_sel:[1,0] op_sel_hi:[0,1]
	v_pk_fma_f32 v[60:61], v[2:3], v[4:5], v[58:59] op_sel_hi:[1,0,1] neg_lo:[0,0,1] neg_hi:[0,0,1]
	v_pk_fma_f32 v[4:5], v[2:3], v[4:5], v[58:59] op_sel_hi:[1,0,1]
	v_mov_b32_e32 v58, v60
	v_mov_b32_e32 v59, v5
	v_pk_mov_b32 v[62:63], v[4:5], v[60:61] op_sel:[1,0]
	v_mul_f32_e32 v4, v3, v5
	v_pk_fma_f32 v[4:5], v[2:3], v[58:59], v[4:5] op_sel_hi:[1,1,0] neg_lo:[0,0,1] neg_hi:[0,0,1]
	v_pk_mul_f32 v[58:59], v[2:3], v[62:63]
	v_mov_b32_e32 v61, v4
	v_pk_add_f32 v[58:59], v[58:59], v[58:59] op_sel:[0,1] op_sel_hi:[0,1]
	v_pk_mul_f32 v[58:59], v[2:3], v[58:59] op_sel:[1,0] op_sel_hi:[0,1]
	v_pk_add_f32 v[22:23], v[22:23], v[60:61]
	v_pk_fma_f32 v[60:61], v[2:3], v[4:5], v[58:59] op_sel_hi:[1,0,1] neg_lo:[0,0,1] neg_hi:[0,0,1]
	v_pk_fma_f32 v[4:5], v[2:3], v[4:5], v[58:59] op_sel_hi:[1,0,1]
	s_nop 0
	v_mov_b32_e32 v61, v5
	v_mul_f32_e32 v4, v2, v60
	v_pk_fma_f32 v[2:3], v[2:3], v[60:61], v[4:5] op_sel_hi:[1,1,0] neg_lo:[1,0,0] neg_hi:[1,0,0]
	s_nop 0
	v_mov_b32_e32 v61, v3
	v_pk_add_f32 v[20:21], v[20:21], v[60:61]
	ds_read_b128 v[2:5], v56
	v_add_u32_e32 v56, 16, v56
	v_mov_b32_e32 v58, v69
	v_mov_b32_e32 v60, v73
	v_mov_b32_e32 v62, v77
	v_mov_b32_e32 v64, v81
	s_waitcnt lgkmcnt(0)
	v_pk_mul_f32 v[58:59], v[4:5], v[58:59] op_sel_hi:[1,0]
	v_pk_fma_f32 v[66:67], v[4:5], v[60:61], v[58:59] op_sel:[1,0,0] op_sel_hi:[0,0,1]
	v_pk_fma_f32 v[4:5], v[4:5], v[60:61], v[58:59] op_sel:[1,0,0] op_sel_hi:[0,0,1] neg_lo:[0,0,1] neg_hi:[0,0,1]
	v_mov_b32_e32 v59, v5
	v_pk_mov_b32 v[4:5], v[4:5], v[66:67] op_sel:[1,0]
	v_mov_b32_e32 v58, v66
	v_pk_mul_f32 v[4:5], v[4:5], v[62:63] op_sel_hi:[1,0]
	v_pk_fma_f32 v[60:61], v[64:65], v[58:59], v[4:5] op_sel_hi:[0,1,1]
	v_pk_fma_f32 v[4:5], v[64:65], v[58:59], v[4:5] op_sel_hi:[0,1,1] neg_lo:[0,0,1] neg_hi:[0,0,1]
	v_mov_b32_e32 v58, v60
	v_mov_b32_e32 v59, v5
	v_pk_mov_b32 v[62:63], v[4:5], v[60:61] op_sel:[1,0]
	v_mul_f32_e32 v60, v3, v60
	v_pk_fma_f32 v[60:61], v[2:3], v[62:63], v[60:61] op_sel_hi:[1,1,0] neg_lo:[0,0,1] neg_hi:[0,0,1]
	v_pk_mul_f32 v[58:59], v[2:3], v[58:59]
	v_pk_mov_b32 v[4:5], v[4:5], v[60:61] op_sel:[1,0]
	v_pk_add_f32 v[58:59], v[58:59], v[58:59] op_sel:[0,1] op_sel_hi:[0,1]
	v_pk_add_f32 v[40:41], v[40:41], v[4:5]
	v_pk_mul_f32 v[4:5], v[2:3], v[58:59]
	s_nop 0
	v_pk_fma_f32 v[58:59], v[2:3], v[60:61], v[4:5] op_sel:[1,0,0] op_sel_hi:[0,0,1]
	v_pk_fma_f32 v[4:5], v[2:3], v[60:61], v[4:5] op_sel:[1,0,0] op_sel_hi:[0,0,1] neg_lo:[0,0,1] neg_hi:[0,0,1]
	v_mov_b32_e32 v60, v58
	v_mov_b32_e32 v61, v5
	v_pk_mov_b32 v[62:63], v[4:5], v[58:59] op_sel:[1,0]
	v_mul_f32_e32 v58, v3, v58
	v_pk_fma_f32 v[58:59], v[2:3], v[62:63], v[58:59] op_sel_hi:[1,1,0] neg_lo:[0,0,1] neg_hi:[0,0,1]
	v_pk_mul_f32 v[60:61], v[2:3], v[60:61]
	v_pk_mov_b32 v[4:5], v[4:5], v[58:59] op_sel:[1,0]
	v_pk_add_f32 v[60:61], v[60:61], v[60:61] op_sel:[0,1] op_sel_hi:[0,1]
	v_pk_add_f32 v[38:39], v[38:39], v[4:5]
	v_pk_mul_f32 v[4:5], v[2:3], v[60:61]
	s_nop 0
	v_pk_fma_f32 v[60:61], v[2:3], v[58:59], v[4:5] op_sel:[1,0,0] op_sel_hi:[0,0,1]
	v_pk_fma_f32 v[4:5], v[2:3], v[58:59], v[4:5] op_sel:[1,0,0] op_sel_hi:[0,0,1] neg_lo:[0,0,1] neg_hi:[0,0,1]
	v_mov_b32_e32 v58, v60
	v_mov_b32_e32 v59, v5
	v_pk_mov_b32 v[62:63], v[4:5], v[60:61] op_sel:[1,0]
	v_mul_f32_e32 v60, v3, v60
	v_pk_fma_f32 v[60:61], v[2:3], v[62:63], v[60:61] op_sel_hi:[1,1,0] neg_lo:[0,0,1] neg_hi:[0,0,1]
	v_pk_mul_f32 v[58:59], v[2:3], v[58:59]
	v_pk_mov_b32 v[4:5], v[4:5], v[60:61] op_sel:[1,0]
	v_pk_add_f32 v[58:59], v[58:59], v[58:59] op_sel:[0,1] op_sel_hi:[0,1]
	v_pk_add_f32 v[34:35], v[34:35], v[4:5]
	v_pk_mul_f32 v[4:5], v[2:3], v[58:59]
	s_nop 0
	v_pk_fma_f32 v[58:59], v[2:3], v[60:61], v[4:5] op_sel:[1,0,0] op_sel_hi:[0,0,1]
	v_pk_fma_f32 v[4:5], v[2:3], v[60:61], v[4:5] op_sel:[1,0,0] op_sel_hi:[0,0,1] neg_lo:[0,0,1] neg_hi:[0,0,1]
	v_mov_b32_e32 v60, v58
	v_mov_b32_e32 v61, v5
	v_pk_mov_b32 v[62:63], v[4:5], v[58:59] op_sel:[1,0]
	v_mul_f32_e32 v58, v3, v58
	v_pk_fma_f32 v[58:59], v[2:3], v[62:63], v[58:59] op_sel_hi:[1,1,0] neg_lo:[0,0,1] neg_hi:[0,0,1]
	v_pk_mul_f32 v[60:61], v[2:3], v[60:61]
	v_pk_mov_b32 v[4:5], v[4:5], v[58:59] op_sel:[1,0]
	v_pk_add_f32 v[60:61], v[60:61], v[60:61] op_sel:[0,1] op_sel_hi:[0,1]
	v_pk_add_f32 v[32:33], v[32:33], v[4:5]
	v_pk_mul_f32 v[4:5], v[2:3], v[60:61]
	s_nop 0
	v_pk_fma_f32 v[60:61], v[2:3], v[58:59], v[4:5] op_sel:[1,0,0] op_sel_hi:[0,0,1]
	v_pk_fma_f32 v[4:5], v[2:3], v[58:59], v[4:5] op_sel:[1,0,0] op_sel_hi:[0,0,1] neg_lo:[0,0,1] neg_hi:[0,0,1]
	v_mov_b32_e32 v58, v60
	v_mov_b32_e32 v59, v5
	v_pk_mov_b32 v[62:63], v[4:5], v[60:61] op_sel:[1,0]
	v_mul_f32_e32 v60, v3, v60
	v_pk_fma_f32 v[60:61], v[2:3], v[62:63], v[60:61] op_sel_hi:[1,1,0] neg_lo:[0,0,1] neg_hi:[0,0,1]
	v_pk_mul_f32 v[58:59], v[2:3], v[58:59]
	v_pk_mov_b32 v[4:5], v[4:5], v[60:61] op_sel:[1,0]
	v_pk_add_f32 v[58:59], v[58:59], v[58:59] op_sel:[0,1] op_sel_hi:[0,1]
	v_pk_add_f32 v[26:27], v[26:27], v[4:5]
	v_pk_mul_f32 v[4:5], v[2:3], v[58:59] op_sel:[1,0] op_sel_hi:[0,1]
	v_pk_fma_f32 v[58:59], v[2:3], v[60:61], v[4:5] op_sel_hi:[1,0,1] neg_lo:[0,0,1] neg_hi:[0,0,1]
	v_pk_fma_f32 v[4:5], v[2:3], v[60:61], v[4:5] op_sel_hi:[1,0,1]
	v_mov_b32_e32 v60, v58
	v_mov_b32_e32 v61, v5
	v_pk_mov_b32 v[62:63], v[4:5], v[58:59] op_sel:[1,0]
	v_mul_f32_e32 v4, v3, v5
	v_pk_fma_f32 v[4:5], v[2:3], v[60:61], v[4:5] op_sel_hi:[1,1,0] neg_lo:[0,0,1] neg_hi:[0,0,1]
	v_pk_mul_f32 v[60:61], v[2:3], v[62:63]
	v_mov_b32_e32 v59, v4
	v_pk_add_f32 v[60:61], v[60:61], v[60:61] op_sel:[0,1] op_sel_hi:[0,1]
	v_pk_add_f32 v[24:25], v[24:25], v[58:59]
	v_pk_mul_f32 v[58:59], v[2:3], v[60:61] op_sel:[1,0] op_sel_hi:[0,1]
	v_pk_fma_f32 v[60:61], v[2:3], v[4:5], v[58:59] op_sel_hi:[1,0,1] neg_lo:[0,0,1] neg_hi:[0,0,1]
	v_pk_fma_f32 v[4:5], v[2:3], v[4:5], v[58:59] op_sel_hi:[1,0,1]
	v_mov_b32_e32 v58, v60
	v_mov_b32_e32 v59, v5
	v_pk_mov_b32 v[62:63], v[4:5], v[60:61] op_sel:[1,0]
	v_mul_f32_e32 v4, v3, v5
	v_pk_fma_f32 v[4:5], v[2:3], v[58:59], v[4:5] op_sel_hi:[1,1,0] neg_lo:[0,0,1] neg_hi:[0,0,1]
	v_pk_mul_f32 v[58:59], v[2:3], v[62:63]
	v_mov_b32_e32 v61, v4
	v_pk_add_f32 v[58:59], v[58:59], v[58:59] op_sel:[0,1] op_sel_hi:[0,1]
	v_pk_mul_f32 v[58:59], v[2:3], v[58:59] op_sel:[1,0] op_sel_hi:[0,1]
	v_pk_add_f32 v[22:23], v[22:23], v[60:61]
	v_pk_fma_f32 v[60:61], v[2:3], v[4:5], v[58:59] op_sel_hi:[1,0,1] neg_lo:[0,0,1] neg_hi:[0,0,1]
	v_pk_fma_f32 v[4:5], v[2:3], v[4:5], v[58:59] op_sel_hi:[1,0,1]
	s_nop 0
	v_mov_b32_e32 v61, v5
	v_mul_f32_e32 v4, v2, v60
	v_pk_fma_f32 v[2:3], v[2:3], v[60:61], v[4:5] op_sel_hi:[1,1,0] neg_lo:[1,0,0] neg_hi:[1,0,0]
	s_nop 0
	v_mov_b32_e32 v61, v3
	v_pk_add_f32 v[20:21], v[20:21], v[60:61]
	ds_read_b128 v[2:5], v56
	v_add_u32_e32 v56, 16, v56
	v_mov_b32_e32 v58, v70
	v_mov_b32_e32 v60, v74
	v_mov_b32_e32 v62, v78
	v_mov_b32_e32 v64, v82
	s_waitcnt lgkmcnt(0)
	v_pk_mul_f32 v[58:59], v[4:5], v[58:59] op_sel_hi:[1,0]
	v_pk_fma_f32 v[66:67], v[4:5], v[60:61], v[58:59] op_sel:[1,0,0] op_sel_hi:[0,0,1]
	v_pk_fma_f32 v[4:5], v[4:5], v[60:61], v[58:59] op_sel:[1,0,0] op_sel_hi:[0,0,1] neg_lo:[0,0,1] neg_hi:[0,0,1]
	v_mov_b32_e32 v59, v5
	v_pk_mov_b32 v[4:5], v[4:5], v[66:67] op_sel:[1,0]
	v_mov_b32_e32 v58, v66
	v_pk_mul_f32 v[4:5], v[4:5], v[62:63] op_sel_hi:[1,0]
	v_pk_fma_f32 v[60:61], v[64:65], v[58:59], v[4:5] op_sel_hi:[0,1,1]
	v_pk_fma_f32 v[4:5], v[64:65], v[58:59], v[4:5] op_sel_hi:[0,1,1] neg_lo:[0,0,1] neg_hi:[0,0,1]
	v_mov_b32_e32 v58, v60
	v_mov_b32_e32 v59, v5
	v_pk_mov_b32 v[62:63], v[4:5], v[60:61] op_sel:[1,0]
	v_mul_f32_e32 v60, v3, v60
	v_pk_fma_f32 v[60:61], v[2:3], v[62:63], v[60:61] op_sel_hi:[1,1,0] neg_lo:[0,0,1] neg_hi:[0,0,1]
	v_pk_mul_f32 v[58:59], v[2:3], v[58:59]
	v_pk_mov_b32 v[4:5], v[4:5], v[60:61] op_sel:[1,0]
	v_pk_add_f32 v[58:59], v[58:59], v[58:59] op_sel:[0,1] op_sel_hi:[0,1]
	v_pk_add_f32 v[40:41], v[40:41], v[4:5]
	v_pk_mul_f32 v[4:5], v[2:3], v[58:59]
	s_nop 0
	v_pk_fma_f32 v[58:59], v[2:3], v[60:61], v[4:5] op_sel:[1,0,0] op_sel_hi:[0,0,1]
	v_pk_fma_f32 v[4:5], v[2:3], v[60:61], v[4:5] op_sel:[1,0,0] op_sel_hi:[0,0,1] neg_lo:[0,0,1] neg_hi:[0,0,1]
	v_mov_b32_e32 v60, v58
	v_mov_b32_e32 v61, v5
	v_pk_mov_b32 v[62:63], v[4:5], v[58:59] op_sel:[1,0]
	v_mul_f32_e32 v58, v3, v58
	v_pk_fma_f32 v[58:59], v[2:3], v[62:63], v[58:59] op_sel_hi:[1,1,0] neg_lo:[0,0,1] neg_hi:[0,0,1]
	v_pk_mul_f32 v[60:61], v[2:3], v[60:61]
	v_pk_mov_b32 v[4:5], v[4:5], v[58:59] op_sel:[1,0]
	v_pk_add_f32 v[60:61], v[60:61], v[60:61] op_sel:[0,1] op_sel_hi:[0,1]
	v_pk_add_f32 v[38:39], v[38:39], v[4:5]
	v_pk_mul_f32 v[4:5], v[2:3], v[60:61]
	s_nop 0
	v_pk_fma_f32 v[60:61], v[2:3], v[58:59], v[4:5] op_sel:[1,0,0] op_sel_hi:[0,0,1]
	v_pk_fma_f32 v[4:5], v[2:3], v[58:59], v[4:5] op_sel:[1,0,0] op_sel_hi:[0,0,1] neg_lo:[0,0,1] neg_hi:[0,0,1]
	v_mov_b32_e32 v58, v60
	v_mov_b32_e32 v59, v5
	v_pk_mov_b32 v[62:63], v[4:5], v[60:61] op_sel:[1,0]
	v_mul_f32_e32 v60, v3, v60
	v_pk_fma_f32 v[60:61], v[2:3], v[62:63], v[60:61] op_sel_hi:[1,1,0] neg_lo:[0,0,1] neg_hi:[0,0,1]
	v_pk_mul_f32 v[58:59], v[2:3], v[58:59]
	v_pk_mov_b32 v[4:5], v[4:5], v[60:61] op_sel:[1,0]
	v_pk_add_f32 v[58:59], v[58:59], v[58:59] op_sel:[0,1] op_sel_hi:[0,1]
	v_pk_add_f32 v[34:35], v[34:35], v[4:5]
	v_pk_mul_f32 v[4:5], v[2:3], v[58:59]
	s_nop 0
	v_pk_fma_f32 v[58:59], v[2:3], v[60:61], v[4:5] op_sel:[1,0,0] op_sel_hi:[0,0,1]
	v_pk_fma_f32 v[4:5], v[2:3], v[60:61], v[4:5] op_sel:[1,0,0] op_sel_hi:[0,0,1] neg_lo:[0,0,1] neg_hi:[0,0,1]
	v_mov_b32_e32 v60, v58
	v_mov_b32_e32 v61, v5
	v_pk_mov_b32 v[62:63], v[4:5], v[58:59] op_sel:[1,0]
	v_mul_f32_e32 v58, v3, v58
	v_pk_fma_f32 v[58:59], v[2:3], v[62:63], v[58:59] op_sel_hi:[1,1,0] neg_lo:[0,0,1] neg_hi:[0,0,1]
	v_pk_mul_f32 v[60:61], v[2:3], v[60:61]
	v_pk_mov_b32 v[4:5], v[4:5], v[58:59] op_sel:[1,0]
	v_pk_add_f32 v[60:61], v[60:61], v[60:61] op_sel:[0,1] op_sel_hi:[0,1]
	v_pk_add_f32 v[32:33], v[32:33], v[4:5]
	v_pk_mul_f32 v[4:5], v[2:3], v[60:61]
	s_nop 0
	v_pk_fma_f32 v[60:61], v[2:3], v[58:59], v[4:5] op_sel:[1,0,0] op_sel_hi:[0,0,1]
	v_pk_fma_f32 v[4:5], v[2:3], v[58:59], v[4:5] op_sel:[1,0,0] op_sel_hi:[0,0,1] neg_lo:[0,0,1] neg_hi:[0,0,1]
	v_mov_b32_e32 v58, v60
	v_mov_b32_e32 v59, v5
	v_pk_mov_b32 v[62:63], v[4:5], v[60:61] op_sel:[1,0]
	v_mul_f32_e32 v60, v3, v60
	v_pk_fma_f32 v[60:61], v[2:3], v[62:63], v[60:61] op_sel_hi:[1,1,0] neg_lo:[0,0,1] neg_hi:[0,0,1]
	v_pk_mul_f32 v[58:59], v[2:3], v[58:59]
	v_pk_mov_b32 v[4:5], v[4:5], v[60:61] op_sel:[1,0]
	v_pk_add_f32 v[58:59], v[58:59], v[58:59] op_sel:[0,1] op_sel_hi:[0,1]
	v_pk_add_f32 v[26:27], v[26:27], v[4:5]
	v_pk_mul_f32 v[4:5], v[2:3], v[58:59] op_sel:[1,0] op_sel_hi:[0,1]
	v_pk_fma_f32 v[58:59], v[2:3], v[60:61], v[4:5] op_sel_hi:[1,0,1] neg_lo:[0,0,1] neg_hi:[0,0,1]
	v_pk_fma_f32 v[4:5], v[2:3], v[60:61], v[4:5] op_sel_hi:[1,0,1]
	v_mov_b32_e32 v60, v58
	v_mov_b32_e32 v61, v5
	v_pk_mov_b32 v[62:63], v[4:5], v[58:59] op_sel:[1,0]
	v_mul_f32_e32 v4, v3, v5
	v_pk_fma_f32 v[4:5], v[2:3], v[60:61], v[4:5] op_sel_hi:[1,1,0] neg_lo:[0,0,1] neg_hi:[0,0,1]
	v_pk_mul_f32 v[60:61], v[2:3], v[62:63]
	v_mov_b32_e32 v59, v4
	v_pk_add_f32 v[60:61], v[60:61], v[60:61] op_sel:[0,1] op_sel_hi:[0,1]
	v_pk_add_f32 v[24:25], v[24:25], v[58:59]
	v_pk_mul_f32 v[58:59], v[2:3], v[60:61] op_sel:[1,0] op_sel_hi:[0,1]
	v_pk_fma_f32 v[60:61], v[2:3], v[4:5], v[58:59] op_sel_hi:[1,0,1] neg_lo:[0,0,1] neg_hi:[0,0,1]
	v_pk_fma_f32 v[4:5], v[2:3], v[4:5], v[58:59] op_sel_hi:[1,0,1]
	v_mov_b32_e32 v58, v60
	v_mov_b32_e32 v59, v5
	v_pk_mov_b32 v[62:63], v[4:5], v[60:61] op_sel:[1,0]
	v_mul_f32_e32 v4, v3, v5
	v_pk_fma_f32 v[4:5], v[2:3], v[58:59], v[4:5] op_sel_hi:[1,1,0] neg_lo:[0,0,1] neg_hi:[0,0,1]
	v_pk_mul_f32 v[58:59], v[2:3], v[62:63]
	v_mov_b32_e32 v61, v4
	v_pk_add_f32 v[58:59], v[58:59], v[58:59] op_sel:[0,1] op_sel_hi:[0,1]
	v_pk_mul_f32 v[58:59], v[2:3], v[58:59] op_sel:[1,0] op_sel_hi:[0,1]
	v_pk_add_f32 v[22:23], v[22:23], v[60:61]
	v_pk_fma_f32 v[60:61], v[2:3], v[4:5], v[58:59] op_sel_hi:[1,0,1] neg_lo:[0,0,1] neg_hi:[0,0,1]
	v_pk_fma_f32 v[4:5], v[2:3], v[4:5], v[58:59] op_sel_hi:[1,0,1]
	s_nop 0
	v_mov_b32_e32 v61, v5
	v_mul_f32_e32 v4, v2, v60
	v_pk_fma_f32 v[2:3], v[2:3], v[60:61], v[4:5] op_sel_hi:[1,1,0] neg_lo:[1,0,0] neg_hi:[1,0,0]
	s_nop 0
	v_mov_b32_e32 v61, v3
	v_pk_add_f32 v[20:21], v[20:21], v[60:61]
	ds_read_b128 v[2:5], v56
	v_add_u32_e32 v56, 16, v56
	v_mov_b32_e32 v58, v71
	v_mov_b32_e32 v60, v75
	v_mov_b32_e32 v62, v79
	v_mov_b32_e32 v64, v83
	s_waitcnt lgkmcnt(0)
	v_pk_mul_f32 v[58:59], v[4:5], v[58:59] op_sel_hi:[1,0]
	v_pk_fma_f32 v[66:67], v[4:5], v[60:61], v[58:59] op_sel:[1,0,0] op_sel_hi:[0,0,1]
	v_pk_fma_f32 v[4:5], v[4:5], v[60:61], v[58:59] op_sel:[1,0,0] op_sel_hi:[0,0,1] neg_lo:[0,0,1] neg_hi:[0,0,1]
	v_mov_b32_e32 v59, v5
	v_pk_mov_b32 v[4:5], v[4:5], v[66:67] op_sel:[1,0]
	v_mov_b32_e32 v58, v66
	v_pk_mul_f32 v[4:5], v[4:5], v[62:63] op_sel_hi:[1,0]
	v_pk_fma_f32 v[60:61], v[64:65], v[58:59], v[4:5] op_sel_hi:[0,1,1]
	v_pk_fma_f32 v[4:5], v[64:65], v[58:59], v[4:5] op_sel_hi:[0,1,1] neg_lo:[0,0,1] neg_hi:[0,0,1]
	v_mov_b32_e32 v58, v60
	v_mov_b32_e32 v59, v5
	v_pk_mov_b32 v[62:63], v[4:5], v[60:61] op_sel:[1,0]
	v_mul_f32_e32 v60, v3, v60
	v_pk_fma_f32 v[60:61], v[2:3], v[62:63], v[60:61] op_sel_hi:[1,1,0] neg_lo:[0,0,1] neg_hi:[0,0,1]
	v_pk_mul_f32 v[58:59], v[2:3], v[58:59]
	v_pk_mov_b32 v[4:5], v[4:5], v[60:61] op_sel:[1,0]
	v_pk_add_f32 v[58:59], v[58:59], v[58:59] op_sel:[0,1] op_sel_hi:[0,1]
	v_pk_add_f32 v[40:41], v[40:41], v[4:5]
	v_pk_mul_f32 v[4:5], v[2:3], v[58:59]
	s_nop 0
	v_pk_fma_f32 v[58:59], v[2:3], v[60:61], v[4:5] op_sel:[1,0,0] op_sel_hi:[0,0,1]
	v_pk_fma_f32 v[4:5], v[2:3], v[60:61], v[4:5] op_sel:[1,0,0] op_sel_hi:[0,0,1] neg_lo:[0,0,1] neg_hi:[0,0,1]
	v_mov_b32_e32 v60, v58
	v_mov_b32_e32 v61, v5
	v_pk_mov_b32 v[62:63], v[4:5], v[58:59] op_sel:[1,0]
	v_mul_f32_e32 v58, v3, v58
	v_pk_fma_f32 v[58:59], v[2:3], v[62:63], v[58:59] op_sel_hi:[1,1,0] neg_lo:[0,0,1] neg_hi:[0,0,1]
	v_pk_mul_f32 v[60:61], v[2:3], v[60:61]
	v_pk_mov_b32 v[4:5], v[4:5], v[58:59] op_sel:[1,0]
	v_pk_add_f32 v[60:61], v[60:61], v[60:61] op_sel:[0,1] op_sel_hi:[0,1]
	v_pk_add_f32 v[38:39], v[38:39], v[4:5]
	v_pk_mul_f32 v[4:5], v[2:3], v[60:61]
	s_nop 0
	v_pk_fma_f32 v[60:61], v[2:3], v[58:59], v[4:5] op_sel:[1,0,0] op_sel_hi:[0,0,1]
	v_pk_fma_f32 v[4:5], v[2:3], v[58:59], v[4:5] op_sel:[1,0,0] op_sel_hi:[0,0,1] neg_lo:[0,0,1] neg_hi:[0,0,1]
	v_mov_b32_e32 v58, v60
	v_mov_b32_e32 v59, v5
	v_pk_mov_b32 v[62:63], v[4:5], v[60:61] op_sel:[1,0]
	v_mul_f32_e32 v60, v3, v60
	v_pk_fma_f32 v[60:61], v[2:3], v[62:63], v[60:61] op_sel_hi:[1,1,0] neg_lo:[0,0,1] neg_hi:[0,0,1]
	v_pk_mul_f32 v[58:59], v[2:3], v[58:59]
	v_pk_mov_b32 v[4:5], v[4:5], v[60:61] op_sel:[1,0]
	v_pk_add_f32 v[58:59], v[58:59], v[58:59] op_sel:[0,1] op_sel_hi:[0,1]
	v_pk_add_f32 v[34:35], v[34:35], v[4:5]
	v_pk_mul_f32 v[4:5], v[2:3], v[58:59]
	s_nop 0
	v_pk_fma_f32 v[58:59], v[2:3], v[60:61], v[4:5] op_sel:[1,0,0] op_sel_hi:[0,0,1]
	v_pk_fma_f32 v[4:5], v[2:3], v[60:61], v[4:5] op_sel:[1,0,0] op_sel_hi:[0,0,1] neg_lo:[0,0,1] neg_hi:[0,0,1]
	v_mov_b32_e32 v60, v58
	v_mov_b32_e32 v61, v5
	v_pk_mov_b32 v[62:63], v[4:5], v[58:59] op_sel:[1,0]
	v_mul_f32_e32 v58, v3, v58
	v_pk_fma_f32 v[58:59], v[2:3], v[62:63], v[58:59] op_sel_hi:[1,1,0] neg_lo:[0,0,1] neg_hi:[0,0,1]
	v_pk_mul_f32 v[60:61], v[2:3], v[60:61]
	v_pk_mov_b32 v[4:5], v[4:5], v[58:59] op_sel:[1,0]
	v_pk_add_f32 v[60:61], v[60:61], v[60:61] op_sel:[0,1] op_sel_hi:[0,1]
	v_pk_add_f32 v[32:33], v[32:33], v[4:5]
	v_pk_mul_f32 v[4:5], v[2:3], v[60:61]
	s_nop 0
	v_pk_fma_f32 v[60:61], v[2:3], v[58:59], v[4:5] op_sel:[1,0,0] op_sel_hi:[0,0,1]
	v_pk_fma_f32 v[4:5], v[2:3], v[58:59], v[4:5] op_sel:[1,0,0] op_sel_hi:[0,0,1] neg_lo:[0,0,1] neg_hi:[0,0,1]
	v_mov_b32_e32 v58, v60
	v_mov_b32_e32 v59, v5
	v_pk_mov_b32 v[62:63], v[4:5], v[60:61] op_sel:[1,0]
	v_mul_f32_e32 v60, v3, v60
	v_pk_fma_f32 v[60:61], v[2:3], v[62:63], v[60:61] op_sel_hi:[1,1,0] neg_lo:[0,0,1] neg_hi:[0,0,1]
	v_pk_mul_f32 v[58:59], v[2:3], v[58:59]
	v_pk_mov_b32 v[4:5], v[4:5], v[60:61] op_sel:[1,0]
	v_pk_add_f32 v[58:59], v[58:59], v[58:59] op_sel:[0,1] op_sel_hi:[0,1]
	v_pk_add_f32 v[26:27], v[26:27], v[4:5]
	v_pk_mul_f32 v[4:5], v[2:3], v[58:59] op_sel:[1,0] op_sel_hi:[0,1]
	v_pk_fma_f32 v[58:59], v[2:3], v[60:61], v[4:5] op_sel_hi:[1,0,1] neg_lo:[0,0,1] neg_hi:[0,0,1]
	v_pk_fma_f32 v[4:5], v[2:3], v[60:61], v[4:5] op_sel_hi:[1,0,1]
	v_mov_b32_e32 v60, v58
	v_mov_b32_e32 v61, v5
	v_pk_mov_b32 v[62:63], v[4:5], v[58:59] op_sel:[1,0]
	v_mul_f32_e32 v4, v3, v5
	v_pk_fma_f32 v[4:5], v[2:3], v[60:61], v[4:5] op_sel_hi:[1,1,0] neg_lo:[0,0,1] neg_hi:[0,0,1]
	v_pk_mul_f32 v[60:61], v[2:3], v[62:63]
	v_mov_b32_e32 v59, v4
	v_pk_add_f32 v[60:61], v[60:61], v[60:61] op_sel:[0,1] op_sel_hi:[0,1]
	v_pk_add_f32 v[24:25], v[24:25], v[58:59]
	v_pk_mul_f32 v[58:59], v[2:3], v[60:61] op_sel:[1,0] op_sel_hi:[0,1]
	v_pk_fma_f32 v[60:61], v[2:3], v[4:5], v[58:59] op_sel_hi:[1,0,1] neg_lo:[0,0,1] neg_hi:[0,0,1]
	v_pk_fma_f32 v[4:5], v[2:3], v[4:5], v[58:59] op_sel_hi:[1,0,1]
	v_mov_b32_e32 v58, v60
	v_mov_b32_e32 v59, v5
	v_pk_mov_b32 v[62:63], v[4:5], v[60:61] op_sel:[1,0]
	v_mul_f32_e32 v4, v3, v5
	v_pk_fma_f32 v[4:5], v[2:3], v[58:59], v[4:5] op_sel_hi:[1,1,0] neg_lo:[0,0,1] neg_hi:[0,0,1]
	v_pk_mul_f32 v[58:59], v[2:3], v[62:63]
	v_mov_b32_e32 v61, v4
	v_pk_add_f32 v[58:59], v[58:59], v[58:59] op_sel:[0,1] op_sel_hi:[0,1]
	v_pk_mul_f32 v[58:59], v[2:3], v[58:59] op_sel:[1,0] op_sel_hi:[0,1]
	v_pk_add_f32 v[22:23], v[22:23], v[60:61]
	v_pk_fma_f32 v[60:61], v[2:3], v[4:5], v[58:59] op_sel_hi:[1,0,1] neg_lo:[0,0,1] neg_hi:[0,0,1]
	v_pk_fma_f32 v[4:5], v[2:3], v[4:5], v[58:59] op_sel_hi:[1,0,1]
	s_nop 0
	v_mov_b32_e32 v61, v5
	v_mul_f32_e32 v4, v2, v60
	v_pk_fma_f32 v[2:3], v[2:3], v[60:61], v[4:5] op_sel_hi:[1,1,0] neg_lo:[1,0,0] neg_hi:[1,0,0]
	s_nop 0
	v_mov_b32_e32 v61, v3
	v_pk_add_f32 v[20:21], v[20:21], v[60:61]
	s_cbranch_scc0 .LBB0_419
	v_lshrrev_b32_e32 v2, 8, v8
	v_and_or_b32 v2, v2, 15, v55
	v_ashrrev_i32_e32 v3, 31, v2
	v_lshlrev_b64 v[2:3], 14, v[2:3]
	v_lshl_add_u64 v[2:3], v[10:11], 0, v[2:3]
	v_add_co_u32_e32 v4, vcc, 0x1000, v2
	global_store_dword v[2:3], v40, off
	global_store_dword v[2:3], v41, off offset:1024
	global_store_dword v[2:3], v38, off offset:2048
	global_store_dword v[2:3], v39, off offset:3072
	v_addc_co_u32_e32 v5, vcc, 0, v3, vcc
	global_store_dword v[4:5], v34, off
	global_store_dword v[4:5], v35, off offset:1024
	global_store_dword v[4:5], v32, off offset:2048
	global_store_dword v[4:5], v33, off offset:3072
	v_add_co_u32_e32 v4, vcc, 0x2000, v2
	s_add_i32 s2, s2, s20
	s_nop 0
	v_addc_co_u32_e32 v5, vcc, 0, v3, vcc
	v_add_co_u32_e32 v2, vcc, 0x3000, v2
	s_cmpk_gt_i32 s2, 0x7fff
	s_nop 0
	v_addc_co_u32_e32 v3, vcc, 0, v3, vcc
	v_add_u32_e32 v48, s20, v48
	global_store_dword v[4:5], v26, off
	global_store_dword v[4:5], v27, off offset:1024
	global_store_dword v[4:5], v24, off offset:2048
	global_store_dword v[4:5], v25, off offset:3072
	global_store_dword v[2:3], v22, off
	global_store_dword v[2:3], v23, off offset:1024
	global_store_dword v[2:3], v20, off offset:2048
	global_store_dword v[2:3], v21, off offset:3072
	s_cbranch_scc0 .LBB0_412
